# gates and out K loops also hand-written with HBM->LDS DMA staging (same generator as GEMM-1)
# speedup vs baseline: 1.0804x; 1.0136x over previous
; DEV int tid_() { int t = threadIdx.x; asm volatile("" : "+v"(t)); return t; }
; DEV int bid_() { int b = blockIdx.x; asm volatile("" : "+s"(b)); return b; }
; template <int NI, bool DEEP = true>
; DEV void gemm_tile(f32x16 (&acc)[2][NI], const bf16* __restrict__ A, int lda, const bf16* __restrict__ Bt, int ldb,
;                    int K, bf16* sA, bf16* sB) {
;   int tid = tid_(), lane = tid & 63, wave = tid >> 6;
;   int wm = wave >> 1, wn = wave & 1;
;   int lr = tid >> 3, lc = (tid & 7) * 8;
;   const bf16* Ap = A + (size_t)lr * lda + lc;
;   const bf16* Bp = Bt + (size_t)lr * ldb + lc;
;   u32x4 ra0[4], rb0[2 * NI], ra1[4], rb1[2 * NI];
; __device__ void phase_gemm1(PRef p, bf16* sA, bf16* sB) {
;     ...
;   for (int t = bid_() >> 3; t < 36 * 24; t += per_) {
;     int rt = xcd_ + 8 * (t / 24), ct = t % 24;
;     f32x16 acc[2][2];
;     zero_acc<2>(acc);
;     gemm_tile<2>(acc, p.HY + (size_t)rt * 128 * 1024, 1024, p.WT1 + (size_t)ct * 128 * 1024, 1024, 1024, sA, sB);
.LBB0_305:
	s_mul_hi_i32 s0, s24, 0x2aaaaaab
	s_lshr_b32 s1, s0, 31
	s_ashr_i32 s0, s0, 2
	s_add_i32 s0, s0, s1
	s_lshl_b32 s1, s0, 3
	s_or_b32 s10, s1, s25
	s_mul_i32 s0, s0, 24
	s_sub_i32 s12, s24, s0
	s_lshl_b32 s0, s10, 18
	s_add_u32 s98, s86, s0
	s_addc_u32 s99, s87, 0
	s_lshl_b32 s0, s12, 18
	s_waitcnt lgkmcnt(0)
	s_add_u32 s100, s4, s0
	s_addc_u32 s101, s5, 0
	v_and_b32_e32 v0, 63, v196
	v_lshrrev_b32_e32 v1, 6, v196
	v_lshrrev_b32_e32 v2, 3, v0
	v_readfirstlane_b32 s16, v1
	v_lshrrev_b32_e32 v78, 1, v2
	v_and_b32_e32 v79, 7, v0
	v_xor_b32_e32 v78, v79, v78
	v_lshlrev_b32_e32 v78, 4, v78
	v_lshl_or_b32 v68, v2, 11, v78
	v_xor_b32_e32 v69, 64, v68
	v_lshrrev_b32_e32 v78, 5, v0
	v_bfe_u32 v79, v0, 1, 3
	v_and_b32_e32 v2, 31, v0
	v_lshrrev_b32_e32 v0, 1, v1
	v_and_b32_e32 v1, 1, v1
	v_lshl_add_u32 v0, v0, 6, v2
	v_lshl_add_u32 v1, v1, 6, v2
	v_lshlrev_b32_e32 v0, 7, v0
	v_lshlrev_b32_e32 v1, 7, v1
	v_add_u32_e32 v1, 0x4000, v1
	v_add_u32_e32 v2, 0, v78
	v_xor_b32_e32 v2, v2, v79
	v_lshl_add_u32 v70, v2, 4, v0
	v_lshl_add_u32 v74, v2, 4, v1
	v_add_u32_e32 v2, 2, v78
	v_xor_b32_e32 v2, v2, v79
	v_lshl_add_u32 v71, v2, 4, v0
	v_lshl_add_u32 v75, v2, 4, v1
	v_add_u32_e32 v2, 4, v78
	v_xor_b32_e32 v2, v2, v79
	v_lshl_add_u32 v72, v2, 4, v0
	v_lshl_add_u32 v76, v2, 4, v1
	v_add_u32_e32 v2, 6, v78
	v_xor_b32_e32 v2, v2, v79
	v_lshl_add_u32 v73, v2, 4, v0
	v_lshl_add_u32 v77, v2, 4, v1
	s_lshl_b32 s17, s16, 16
	s_lshl_b32 s16, s16, 12
	s_add_u32 s98, s98, s17
	s_addc_u32 s99, s99, 0
	s_add_u32 s100, s100, s17
	s_addc_u32 s101, s101, 0
	s_waitcnt lgkmcnt(0)
	s_barrier
	s_add_u32 m0, s16, 0x0
	s_nop 0
	global_load_lds_dwordx4 v68, s[98:99]
	s_add_u32 m0, s16, 0x400
	s_add_u32 s14, s98, 0x4000
	s_addc_u32 s15, s99, 0
	global_load_lds_dwordx4 v69, s[14:15]
	s_add_u32 m0, s16, 0x800
	s_add_u32 s14, s98, 0x8000
	s_addc_u32 s15, s99, 0
	global_load_lds_dwordx4 v68, s[14:15]
	s_add_u32 m0, s16, 0xc00
	s_add_u32 s14, s98, 0xc000
	s_addc_u32 s15, s99, 0
	global_load_lds_dwordx4 v69, s[14:15]
	s_add_u32 m0, s16, 0x4000
	s_nop 0
	global_load_lds_dwordx4 v68, s[100:101]
	s_add_u32 m0, s16, 0x4400
	s_add_u32 s14, s100, 0x4000
	s_addc_u32 s15, s101, 0
	global_load_lds_dwordx4 v69, s[14:15]
	s_add_u32 m0, s16, 0x4800
	s_add_u32 s14, s100, 0x8000
	s_addc_u32 s15, s101, 0
	global_load_lds_dwordx4 v68, s[14:15]
	s_add_u32 m0, s16, 0x4c00
	s_add_u32 s14, s100, 0xc000
	s_addc_u32 s15, s101, 0
	global_load_lds_dwordx4 v69, s[14:15]
	s_add_u32 s98, s98, 0x80
	s_addc_u32 s99, s99, 0
	s_add_u32 s100, s100, 0x80
	s_addc_u32 s101, s101, 0
	v_mov_b32_e32 v4, 0
	v_mov_b32_e32 v5, 0
	v_mov_b32_e32 v6, 0
	v_mov_b32_e32 v7, 0
	v_mov_b32_e32 v8, 0
	v_mov_b32_e32 v9, 0
	v_mov_b32_e32 v10, 0
	v_mov_b32_e32 v11, 0
	v_mov_b32_e32 v12, 0
	v_mov_b32_e32 v13, 0
	v_mov_b32_e32 v14, 0
	v_mov_b32_e32 v15, 0
	v_mov_b32_e32 v16, 0
	v_mov_b32_e32 v17, 0
	v_mov_b32_e32 v18, 0
	v_mov_b32_e32 v19, 0
	v_mov_b32_e32 v20, 0
	v_mov_b32_e32 v21, 0
	v_mov_b32_e32 v22, 0
	v_mov_b32_e32 v23, 0
	v_mov_b32_e32 v24, 0
	v_mov_b32_e32 v25, 0
	v_mov_b32_e32 v26, 0
	v_mov_b32_e32 v27, 0
	v_mov_b32_e32 v28, 0
	v_mov_b32_e32 v29, 0
	v_mov_b32_e32 v30, 0
	v_mov_b32_e32 v31, 0
	v_mov_b32_e32 v32, 0
	v_mov_b32_e32 v33, 0
	v_mov_b32_e32 v34, 0
	v_mov_b32_e32 v35, 0
	v_mov_b32_e32 v36, 0
	v_mov_b32_e32 v37, 0
	v_mov_b32_e32 v38, 0
	v_mov_b32_e32 v39, 0
	v_mov_b32_e32 v40, 0
	v_mov_b32_e32 v41, 0
	v_mov_b32_e32 v42, 0
	v_mov_b32_e32 v43, 0
	v_mov_b32_e32 v44, 0
	v_mov_b32_e32 v45, 0
	v_mov_b32_e32 v46, 0
	v_mov_b32_e32 v47, 0
	v_mov_b32_e32 v48, 0
	v_mov_b32_e32 v49, 0
	v_mov_b32_e32 v50, 0
	v_mov_b32_e32 v51, 0
	v_mov_b32_e32 v52, 0
	v_mov_b32_e32 v53, 0
	v_mov_b32_e32 v54, 0
	v_mov_b32_e32 v55, 0
	v_mov_b32_e32 v56, 0
	v_mov_b32_e32 v57, 0
	v_mov_b32_e32 v58, 0
	v_mov_b32_e32 v59, 0
	v_mov_b32_e32 v60, 0
	v_mov_b32_e32 v61, 0
	v_mov_b32_e32 v62, 0
	v_mov_b32_e32 v63, 0
	v_mov_b32_e32 v64, 0
	v_mov_b32_e32 v65, 0
	v_mov_b32_e32 v66, 0
	v_mov_b32_e32 v67, 0
	s_mov_b32 s11, 0

; DEV int tid_() { int t = threadIdx.x; asm volatile("" : "+v"(t)); return t; }
; DEV int bid_() { int b = blockIdx.x; asm volatile("" : "+s"(b)); return b; }
; template <int NI, bool DEEP = true>
; DEV void gemm_tile(f32x16 (&acc)[2][NI], const bf16* __restrict__ A, int lda, const bf16* __restrict__ Bt, int ldb,
;                    int K, bf16* sA, bf16* sB) {
;   int tid = tid_(), lane = tid & 63, wave = tid >> 6;
;   int wm = wave >> 1, wn = wave & 1;
;   int lr = tid >> 3, lc = (tid & 7) * 8;
;   const bf16* Ap = A + (size_t)lr * lda + lc;
;   const bf16* Bp = Bt + (size_t)lr * ldb + lc;
;   u32x4 ra0[4], rb0[2 * NI], ra1[4], rb1[2 * NI];
; __device__ void phase_gates(PRef p, int l, const bf16* H2, bf16* sA, bf16* sB) {
;     ...
;   for (int t = bid_() >> 3; t < 36 * 12; t += per_) {
;     int rt = xcd_ + 8 * (t / 12), ct = t % 12;
;     if (skip_rt(l, rt)) continue;
;     f32x16 acc[2][2];
;     zero_acc<2>(acc);
;     gemm_tile<2>(acc, H2 + (size_t)rt * 128 * 1024, 1024, p.WT2 + (size_t)ct * 128 * 1024, 1024, 1024, sA, sB);
.LBB0_869:
	s_mul_hi_i32 s0, s16, 0x2aaaaaab
	s_lshr_b32 s1, s0, 31
	s_ashr_i32 s0, s0, 1
	s_add_i32 s0, s0, s1
	s_lshl_b32 s1, s0, 3
	s_or_b32 s10, s1, s17
	s_mul_hi_i32 s1, s10, 0x38e38e39
	s_lshr_b32 s11, s1, 31
	s_ashr_i32 s1, s1, 2
	s_add_i32 s1, s1, s11
	s_mul_i32 s1, s1, 18
	s_sub_i32 s1, s10, s1
	s_cmp_lt_i32 s1, 2
	s_cselect_b64 s[12:13], -1, 0
	s_and_b64 s[12:13], s[6:7], s[12:13]
	s_and_b64 vcc, exec, s[12:13]
	s_cbranch_vccnz .LBB0_868
	s_mul_i32 s0, s0, 12
	s_sub_i32 s12, s16, s0
	v_readlane_b32 s14, v245, 4
	v_readlane_b32 s15, v245, 5
	s_lshl_b32 s0, s10, 18
	s_add_u32 s98, s14, s0
	s_addc_u32 s99, s15, 0
	s_lshl_b32 s0, s12, 18
	s_waitcnt lgkmcnt(0)
	s_add_u32 s100, s4, s0
	s_addc_u32 s101, s5, 0
	v_and_b32_e32 v0, 63, v196
	v_lshrrev_b32_e32 v1, 6, v196
	v_lshrrev_b32_e32 v2, 3, v0
	v_readfirstlane_b32 s0, v1
	v_lshrrev_b32_e32 v78, 1, v2
	v_and_b32_e32 v79, 7, v0
	v_xor_b32_e32 v78, v79, v78
	v_lshlrev_b32_e32 v78, 4, v78
	v_lshl_or_b32 v68, v2, 11, v78
	v_xor_b32_e32 v69, 64, v68
	v_lshrrev_b32_e32 v78, 5, v0
	v_bfe_u32 v79, v0, 1, 3
	v_and_b32_e32 v2, 31, v0
	v_lshrrev_b32_e32 v0, 1, v1
	v_and_b32_e32 v1, 1, v1
	v_lshl_add_u32 v0, v0, 6, v2
	v_lshl_add_u32 v1, v1, 6, v2
	v_lshlrev_b32_e32 v0, 7, v0
	v_lshlrev_b32_e32 v1, 7, v1
	v_add_u32_e32 v1, 0x4000, v1
	v_add_u32_e32 v2, 0, v78
	v_xor_b32_e32 v2, v2, v79
	v_lshl_add_u32 v70, v2, 4, v0
	v_lshl_add_u32 v74, v2, 4, v1
	v_add_u32_e32 v2, 2, v78
	v_xor_b32_e32 v2, v2, v79
	v_lshl_add_u32 v71, v2, 4, v0
	v_lshl_add_u32 v75, v2, 4, v1
	v_add_u32_e32 v2, 4, v78
	v_xor_b32_e32 v2, v2, v79
	v_lshl_add_u32 v72, v2, 4, v0
	v_lshl_add_u32 v76, v2, 4, v1
	v_add_u32_e32 v2, 6, v78
	v_xor_b32_e32 v2, v2, v79
	v_lshl_add_u32 v73, v2, 4, v0
	v_lshl_add_u32 v77, v2, 4, v1
	s_lshl_b32 s1, s0, 16
	s_lshl_b32 s0, s0, 12
	s_add_u32 s98, s98, s1
	s_addc_u32 s99, s99, 0
	s_add_u32 s100, s100, s1
	s_addc_u32 s101, s101, 0
	s_waitcnt lgkmcnt(0)
	s_barrier
	s_add_u32 m0, s0, 0x0
	s_nop 0
	global_load_lds_dwordx4 v68, s[98:99]
	s_add_u32 m0, s0, 0x400
	s_add_u32 s14, s98, 0x4000
	s_addc_u32 s15, s99, 0
	global_load_lds_dwordx4 v69, s[14:15]
	s_add_u32 m0, s0, 0x800
	s_add_u32 s14, s98, 0x8000
	s_addc_u32 s15, s99, 0
	global_load_lds_dwordx4 v68, s[14:15]
	s_add_u32 m0, s0, 0xc00
	s_add_u32 s14, s98, 0xc000
	s_addc_u32 s15, s99, 0
	global_load_lds_dwordx4 v69, s[14:15]
	s_add_u32 m0, s0, 0x4000
	s_nop 0
	global_load_lds_dwordx4 v68, s[100:101]
	s_add_u32 m0, s0, 0x4400
	s_add_u32 s14, s100, 0x4000
	s_addc_u32 s15, s101, 0
	global_load_lds_dwordx4 v69, s[14:15]
	s_add_u32 m0, s0, 0x4800
	s_add_u32 s14, s100, 0x8000
	s_addc_u32 s15, s101, 0
	global_load_lds_dwordx4 v68, s[14:15]
	s_add_u32 m0, s0, 0x4c00
	s_add_u32 s14, s100, 0xc000
	s_addc_u32 s15, s101, 0
	global_load_lds_dwordx4 v69, s[14:15]
	s_add_u32 s98, s98, 0x80
	s_addc_u32 s99, s99, 0
	s_add_u32 s100, s100, 0x80
	s_addc_u32 s101, s101, 0
	v_mov_b32_e32 v4, 0
	v_mov_b32_e32 v5, 0
	v_mov_b32_e32 v6, 0
	v_mov_b32_e32 v7, 0
	v_mov_b32_e32 v8, 0
	v_mov_b32_e32 v9, 0
	v_mov_b32_e32 v10, 0
	v_mov_b32_e32 v11, 0
	v_mov_b32_e32 v12, 0
	v_mov_b32_e32 v13, 0
	v_mov_b32_e32 v14, 0
	v_mov_b32_e32 v15, 0
	v_mov_b32_e32 v16, 0
	v_mov_b32_e32 v17, 0
	v_mov_b32_e32 v18, 0
	v_mov_b32_e32 v19, 0
	v_mov_b32_e32 v20, 0
	v_mov_b32_e32 v21, 0
	v_mov_b32_e32 v22, 0
	v_mov_b32_e32 v23, 0
	v_mov_b32_e32 v24, 0
	v_mov_b32_e32 v25, 0
	v_mov_b32_e32 v26, 0
	v_mov_b32_e32 v27, 0
	v_mov_b32_e32 v28, 0
	v_mov_b32_e32 v29, 0
	v_mov_b32_e32 v30, 0
	v_mov_b32_e32 v31, 0
	v_mov_b32_e32 v32, 0
	v_mov_b32_e32 v33, 0
	v_mov_b32_e32 v34, 0
	v_mov_b32_e32 v35, 0
	v_mov_b32_e32 v36, 0
	v_mov_b32_e32 v37, 0
	v_mov_b32_e32 v38, 0
	v_mov_b32_e32 v39, 0
	v_mov_b32_e32 v40, 0
	v_mov_b32_e32 v41, 0
	v_mov_b32_e32 v42, 0
	v_mov_b32_e32 v43, 0
	v_mov_b32_e32 v44, 0
	v_mov_b32_e32 v45, 0
	v_mov_b32_e32 v46, 0
	v_mov_b32_e32 v47, 0
	v_mov_b32_e32 v48, 0
	v_mov_b32_e32 v49, 0
	v_mov_b32_e32 v50, 0
	v_mov_b32_e32 v51, 0
	v_mov_b32_e32 v52, 0
	v_mov_b32_e32 v53, 0
	v_mov_b32_e32 v54, 0
	v_mov_b32_e32 v55, 0
	v_mov_b32_e32 v56, 0
	v_mov_b32_e32 v57, 0
	v_mov_b32_e32 v58, 0
	v_mov_b32_e32 v59, 0
	v_mov_b32_e32 v60, 0
	v_mov_b32_e32 v61, 0
	v_mov_b32_e32 v62, 0
	v_mov_b32_e32 v63, 0
	v_mov_b32_e32 v64, 0
	v_mov_b32_e32 v65, 0
	v_mov_b32_e32 v66, 0
	v_mov_b32_e32 v67, 0
	s_mov_b32 s11, 0
; template <int NI, bool DEEP = true>
; DEV void gemm_tile(f32x16 (&acc)[2][NI], const bf16* __restrict__ A, int lda, const bf16* __restrict__ Bt, int ldb,
;                    int K, bf16* sA, bf16* sB) {
;     ...
;   G_LOAD(ra0, rb0, 0)
;   if (DEEP) {
;     if (64 < K) G_LOAD(ra1, rb1, 64)
;     for (int k0 = 0; k0 < K; k0 += 128) {
;       G_STEP(ra0, rb0, k0 + 128)
;       if (k0 + 64 < K) G_STEP(ra1, rb1, k0 + 192)
;     }
.Lgtk_loop:
	s_waitcnt vmcnt(0)
	s_barrier
	s_add_u32 m0, s0, 0x8000
	s_nop 0
	global_load_lds_dwordx4 v68, s[98:99]
	s_add_u32 m0, s0, 0x8400
	s_add_u32 s14, s98, 0x4000
	s_addc_u32 s15, s99, 0
	global_load_lds_dwordx4 v69, s[14:15]
	s_add_u32 m0, s0, 0x8800
	s_add_u32 s14, s98, 0x8000
	s_addc_u32 s15, s99, 0
	global_load_lds_dwordx4 v68, s[14:15]
	s_add_u32 m0, s0, 0x8c00
	s_add_u32 s14, s98, 0xc000
	s_addc_u32 s15, s99, 0
	global_load_lds_dwordx4 v69, s[14:15]
	s_add_u32 m0, s0, 0xd840
	s_nop 0
	global_load_lds_dwordx4 v68, s[100:101]
	s_add_u32 m0, s0, 0xdc40
	s_add_u32 s14, s100, 0x4000
	s_addc_u32 s15, s101, 0
	global_load_lds_dwordx4 v69, s[14:15]
	s_add_u32 m0, s0, 0xe040
	s_add_u32 s14, s100, 0x8000
	s_addc_u32 s15, s101, 0
	global_load_lds_dwordx4 v68, s[14:15]
	s_add_u32 m0, s0, 0xe440
	s_add_u32 s14, s100, 0xc000
	s_addc_u32 s15, s101, 0
	global_load_lds_dwordx4 v69, s[14:15]
	s_add_u32 s98, s98, 0x80
	s_addc_u32 s99, s99, 0
	s_add_u32 s100, s100, 0x80
	s_addc_u32 s101, s101, 0
	ds_read_b128 v[88:91], v74 offset:0
	ds_read_b128 v[80:83], v70 offset:0
	ds_read_b128 v[84:87], v70 offset:4096
	ds_read_b128 v[92:95], v74 offset:4096
	s_waitcnt lgkmcnt(2)
	v_mfma_f32_32x32x16_bf16 v[52:67], v[88:91], v[80:83], v[52:67]
	ds_read_b128 v[104:107], v75 offset:0
	ds_read_b128 v[96:99], v71 offset:0
	s_waitcnt lgkmcnt(3)
	v_mfma_f32_32x32x16_bf16 v[20:35], v[88:91], v[84:87], v[20:35]
	ds_read_b128 v[100:103], v71 offset:4096
	s_waitcnt lgkmcnt(3)
	v_mfma_f32_32x32x16_bf16 v[36:51], v[92:95], v[80:83], v[36:51]
	ds_read_b128 v[108:111], v75 offset:4096
	v_mfma_f32_32x32x16_bf16 v[4:19], v[92:95], v[84:87], v[4:19]
	s_waitcnt lgkmcnt(2)
	v_mfma_f32_32x32x16_bf16 v[52:67], v[104:107], v[96:99], v[52:67]
	ds_read_b128 v[88:91], v76 offset:0
	ds_read_b128 v[80:83], v72 offset:0
	s_waitcnt lgkmcnt(3)
	v_mfma_f32_32x32x16_bf16 v[20:35], v[104:107], v[100:103], v[20:35]
	ds_read_b128 v[84:87], v72 offset:4096
	s_waitcnt lgkmcnt(3)
	v_mfma_f32_32x32x16_bf16 v[36:51], v[108:111], v[96:99], v[36:51]
	ds_read_b128 v[92:95], v76 offset:4096
	v_mfma_f32_32x32x16_bf16 v[4:19], v[108:111], v[100:103], v[4:19]
	s_waitcnt lgkmcnt(2)
	v_mfma_f32_32x32x16_bf16 v[52:67], v[88:91], v[80:83], v[52:67]
	ds_read_b128 v[104:107], v77 offset:0
	ds_read_b128 v[96:99], v73 offset:0
	s_waitcnt lgkmcnt(3)
	v_mfma_f32_32x32x16_bf16 v[20:35], v[88:91], v[84:87], v[20:35]
	ds_read_b128 v[100:103], v73 offset:4096
	s_waitcnt lgkmcnt(3)
	v_mfma_f32_32x32x16_bf16 v[36:51], v[92:95], v[80:83], v[36:51]
	ds_read_b128 v[108:111], v77 offset:4096
	v_mfma_f32_32x32x16_bf16 v[4:19], v[92:95], v[84:87], v[4:19]
	s_waitcnt lgkmcnt(2)
	v_mfma_f32_32x32x16_bf16 v[52:67], v[104:107], v[96:99], v[52:67]
	s_waitcnt lgkmcnt(1)
	v_mfma_f32_32x32x16_bf16 v[20:35], v[104:107], v[100:103], v[20:35]
	s_waitcnt lgkmcnt(0)
	v_mfma_f32_32x32x16_bf16 v[36:51], v[108:111], v[96:99], v[36:51]
	v_mfma_f32_32x32x16_bf16 v[4:19], v[108:111], v[100:103], v[4:19]
	s_waitcnt vmcnt(0)
	s_barrier
	s_cmp_eq_u32 s11, 7
	s_cbranch_scc1 .Lgtk_nodma
	s_add_u32 m0, s0, 0x0
	s_nop 0
	global_load_lds_dwordx4 v68, s[98:99]
	s_add_u32 m0, s0, 0x400
	s_add_u32 s14, s98, 0x4000
	s_addc_u32 s15, s99, 0
	global_load_lds_dwordx4 v69, s[14:15]
	s_add_u32 m0, s0, 0x800
	s_add_u32 s14, s98, 0x8000
	s_addc_u32 s15, s99, 0
	global_load_lds_dwordx4 v68, s[14:15]
	s_add_u32 m0, s0, 0xc00
	s_add_u32 s14, s98, 0xc000
	s_addc_u32 s15, s99, 0
	global_load_lds_dwordx4 v69, s[14:15]
	s_add_u32 m0, s0, 0x4000
	s_nop 0
	global_load_lds_dwordx4 v68, s[100:101]
	s_add_u32 m0, s0, 0x4400
	s_add_u32 s14, s100, 0x4000
	s_addc_u32 s15, s101, 0
	global_load_lds_dwordx4 v69, s[14:15]
	s_add_u32 m0, s0, 0x4800
	s_add_u32 s14, s100, 0x8000
	s_addc_u32 s15, s101, 0
	global_load_lds_dwordx4 v68, s[14:15]
	s_add_u32 m0, s0, 0x4c00
	s_add_u32 s14, s100, 0xc000
	s_addc_u32 s15, s101, 0
	global_load_lds_dwordx4 v69, s[14:15]
	s_add_u32 s98, s98, 0x80
	s_addc_u32 s99, s99, 0
	s_add_u32 s100, s100, 0x80
	s_addc_u32 s101, s101, 0
.Lgtk_nodma:
	ds_read_b128 v[88:91], v74 offset:38976
	ds_read_b128 v[80:83], v70 offset:32768
	ds_read_b128 v[84:87], v70 offset:36864
	ds_read_b128 v[92:95], v74 offset:43072
	s_waitcnt lgkmcnt(2)
	v_mfma_f32_32x32x16_bf16 v[52:67], v[88:91], v[80:83], v[52:67]
	ds_read_b128 v[104:107], v75 offset:38976
	ds_read_b128 v[96:99], v71 offset:32768
	s_waitcnt lgkmcnt(3)
	v_mfma_f32_32x32x16_bf16 v[20:35], v[88:91], v[84:87], v[20:35]
	ds_read_b128 v[100:103], v71 offset:36864
	s_waitcnt lgkmcnt(3)
	v_mfma_f32_32x32x16_bf16 v[36:51], v[92:95], v[80:83], v[36:51]
	ds_read_b128 v[108:111], v75 offset:43072
	v_mfma_f32_32x32x16_bf16 v[4:19], v[92:95], v[84:87], v[4:19]
	s_waitcnt lgkmcnt(2)
	v_mfma_f32_32x32x16_bf16 v[52:67], v[104:107], v[96:99], v[52:67]
	ds_read_b128 v[88:91], v76 offset:38976
	ds_read_b128 v[80:83], v72 offset:32768
	s_waitcnt lgkmcnt(3)
	v_mfma_f32_32x32x16_bf16 v[20:35], v[104:107], v[100:103], v[20:35]
	ds_read_b128 v[84:87], v72 offset:36864
	s_waitcnt lgkmcnt(3)
	v_mfma_f32_32x32x16_bf16 v[36:51], v[108:111], v[96:99], v[36:51]
	ds_read_b128 v[92:95], v76 offset:43072
	v_mfma_f32_32x32x16_bf16 v[4:19], v[108:111], v[100:103], v[4:19]
	s_waitcnt lgkmcnt(2)
	v_mfma_f32_32x32x16_bf16 v[52:67], v[88:91], v[80:83], v[52:67]
	ds_read_b128 v[104:107], v77 offset:38976
	ds_read_b128 v[96:99], v73 offset:32768
	s_waitcnt lgkmcnt(3)
	v_mfma_f32_32x32x16_bf16 v[20:35], v[88:91], v[84:87], v[20:35]
	ds_read_b128 v[100:103], v73 offset:36864
	s_waitcnt lgkmcnt(3)
	v_mfma_f32_32x32x16_bf16 v[36:51], v[92:95], v[80:83], v[36:51]
	ds_read_b128 v[108:111], v77 offset:43072
	v_mfma_f32_32x32x16_bf16 v[4:19], v[92:95], v[84:87], v[4:19]
	s_waitcnt lgkmcnt(2)
	v_mfma_f32_32x32x16_bf16 v[52:67], v[104:107], v[96:99], v[52:67]
	s_waitcnt lgkmcnt(1)
	v_mfma_f32_32x32x16_bf16 v[20:35], v[104:107], v[100:103], v[20:35]
	s_waitcnt lgkmcnt(0)
	v_mfma_f32_32x32x16_bf16 v[36:51], v[108:111], v[96:99], v[36:51]
	v_mfma_f32_32x32x16_bf16 v[4:19], v[108:111], v[100:103], v[4:19]
	s_add_i32 s11, s11, 1
	s_cmp_lt_u32 s11, 8
	s_cbranch_scc1 .Lgtk_loop
	s_nop 7
	s_nop 7
	s_branch .LBB0_867

; DEV int tid_() { int t = threadIdx.x; asm volatile("" : "+v"(t)); return t; }
; DEV int bid_() { int b = blockIdx.x; asm volatile("" : "+s"(b)); return b; }
; template <int NI, bool DEEP = true>
; DEV void gemm_tile(f32x16 (&acc)[2][NI], const bf16* __restrict__ A, int lda, const bf16* __restrict__ Bt, int ldb,
;                    int K, bf16* sA, bf16* sB) {
;   int tid = tid_(), lane = tid & 63, wave = tid >> 6;
;   int wm = wave >> 1, wn = wave & 1;
;   int lr = tid >> 3, lc = (tid & 7) * 8;
;   const bf16* Ap = A + (size_t)lr * lda + lc;
;   const bf16* Bp = Bt + (size_t)lr * ldb + lc;
;   u32x4 ra0[4], rb0[2 * NI], ra1[4], rb1[2 * NI];
; __device__ void phase_out(PRef p, int l, const bf16* M, const float* xl, const float* xc, bf16* sA, bf16* sB) {
;     ...
;   for (int t = bid_() >> 3; t < 36 * 8; t += per_) {
;     int rt = xcd_ + 8 * (t / 8), ct = t % 8;
;     if (skip_rt(l, rt)) continue;
;     f32x16 acc[2][2];
;     zero_acc<2>(acc);
;     gemm_tile<2>(acc, M + (size_t)rt * 128 * 1024, 1024, p.WOUT + (size_t)ct * 128 * 1024, 1024, 1024, sA, sB);
.LBB0_1082:
	s_ashr_i32 s4, s28, 31
	s_lshr_b32 s4, s4, 29
	s_add_i32 s5, s28, s4
	s_and_b32 s4, s5, -8
	s_or_b32 s4, s4, s34
	s_mul_hi_i32 s14, s4, 0x38e38e39
	s_lshr_b32 s15, s14, 31
	s_ashr_i32 s14, s14, 2
	s_add_i32 s18, s14, s15
	s_mul_i32 s14, s18, 18
	s_sub_i32 s14, s4, s14
	s_cmp_lt_i32 s14, 2
	s_cselect_b64 s[22:23], -1, 0
	s_cmp_gt_i32 s14, 1
	s_cselect_b64 s[24:25], -1, 0
	s_and_b64 s[14:15], s[6:7], s[22:23]
	s_and_b64 vcc, exec, s[14:15]
	s_cbranch_vccnz .LBB0_1081
	s_ashr_i32 s5, s5, 3
	s_lshl_b32 s5, s5, 3
	s_sub_i32 s20, s28, s5
	s_lshl_b32 s14, s4, 18
	s_add_u32 s98, s70, s14
	s_addc_u32 s99, s71, 0
	s_lshl_b32 s14, s20, 18
	s_waitcnt lgkmcnt(0)
	s_add_u32 s100, s12, s14
	s_addc_u32 s101, s13, 0
	v_and_b32_e32 v0, 63, v196
	v_lshrrev_b32_e32 v1, 6, v196
	v_lshrrev_b32_e32 v2, 3, v0
	v_readfirstlane_b32 s16, v1
	v_lshrrev_b32_e32 v78, 1, v2
	v_and_b32_e32 v79, 7, v0
	v_xor_b32_e32 v78, v79, v78
	v_lshlrev_b32_e32 v78, 4, v78
	v_lshl_or_b32 v68, v2, 11, v78
	v_xor_b32_e32 v69, 64, v68
	v_lshrrev_b32_e32 v78, 5, v0
	v_bfe_u32 v79, v0, 1, 3
	v_and_b32_e32 v2, 31, v0
	v_lshrrev_b32_e32 v0, 1, v1
	v_and_b32_e32 v1, 1, v1
	v_lshl_add_u32 v0, v0, 6, v2
	v_lshl_add_u32 v1, v1, 6, v2
	v_lshlrev_b32_e32 v0, 7, v0
	v_lshlrev_b32_e32 v1, 7, v1
	v_add_u32_e32 v1, 0x4000, v1
	v_add_u32_e32 v2, 0, v78
	v_xor_b32_e32 v2, v2, v79
	v_lshl_add_u32 v70, v2, 4, v0
	v_lshl_add_u32 v74, v2, 4, v1
	v_add_u32_e32 v2, 2, v78
	v_xor_b32_e32 v2, v2, v79
	v_lshl_add_u32 v71, v2, 4, v0
	v_lshl_add_u32 v75, v2, 4, v1
	v_add_u32_e32 v2, 4, v78
	v_xor_b32_e32 v2, v2, v79
	v_lshl_add_u32 v72, v2, 4, v0
	v_lshl_add_u32 v76, v2, 4, v1
	v_add_u32_e32 v2, 6, v78
	v_xor_b32_e32 v2, v2, v79
	v_lshl_add_u32 v73, v2, 4, v0
	v_lshl_add_u32 v77, v2, 4, v1
	s_lshl_b32 s17, s16, 16
	s_lshl_b32 s16, s16, 12
	s_add_u32 s98, s98, s17
	s_addc_u32 s99, s99, 0
	s_add_u32 s100, s100, s17
	s_addc_u32 s101, s101, 0
	s_waitcnt lgkmcnt(0)
	s_barrier
	s_add_u32 m0, s16, 0x0
	s_nop 0
	global_load_lds_dwordx4 v68, s[98:99]
	s_add_u32 m0, s16, 0x400
	s_add_u32 s14, s98, 0x4000
	s_addc_u32 s15, s99, 0
	global_load_lds_dwordx4 v69, s[14:15]
	s_add_u32 m0, s16, 0x800
	s_add_u32 s14, s98, 0x8000
	s_addc_u32 s15, s99, 0
	global_load_lds_dwordx4 v68, s[14:15]
	s_add_u32 m0, s16, 0xc00
	s_add_u32 s14, s98, 0xc000
	s_addc_u32 s15, s99, 0
	global_load_lds_dwordx4 v69, s[14:15]
	s_add_u32 m0, s16, 0x4000
	s_nop 0
	global_load_lds_dwordx4 v68, s[100:101]
	s_add_u32 m0, s16, 0x4400
	s_add_u32 s14, s100, 0x4000
	s_addc_u32 s15, s101, 0
	global_load_lds_dwordx4 v69, s[14:15]
	s_add_u32 m0, s16, 0x4800
	s_add_u32 s14, s100, 0x8000
	s_addc_u32 s15, s101, 0
	global_load_lds_dwordx4 v68, s[14:15]
	s_add_u32 m0, s16, 0x4c00
	s_add_u32 s14, s100, 0xc000
	s_addc_u32 s15, s101, 0
	global_load_lds_dwordx4 v69, s[14:15]
	s_add_u32 s98, s98, 0x80
	s_addc_u32 s99, s99, 0
	s_add_u32 s100, s100, 0x80
	s_addc_u32 s101, s101, 0
	v_mov_b32_e32 v4, 0
	v_mov_b32_e32 v5, 0
	v_mov_b32_e32 v6, 0
	v_mov_b32_e32 v7, 0
	v_mov_b32_e32 v8, 0
	v_mov_b32_e32 v9, 0
	v_mov_b32_e32 v10, 0
	v_mov_b32_e32 v11, 0
	v_mov_b32_e32 v12, 0
	v_mov_b32_e32 v13, 0
	v_mov_b32_e32 v14, 0
	v_mov_b32_e32 v15, 0
	v_mov_b32_e32 v16, 0
	v_mov_b32_e32 v17, 0
	v_mov_b32_e32 v18, 0
	v_mov_b32_e32 v19, 0
	v_mov_b32_e32 v20, 0
	v_mov_b32_e32 v21, 0
	v_mov_b32_e32 v22, 0
	v_mov_b32_e32 v23, 0
	v_mov_b32_e32 v24, 0
	v_mov_b32_e32 v25, 0
	v_mov_b32_e32 v26, 0
	v_mov_b32_e32 v27, 0
	v_mov_b32_e32 v28, 0
	v_mov_b32_e32 v29, 0
	v_mov_b32_e32 v30, 0
	v_mov_b32_e32 v31, 0
	v_mov_b32_e32 v32, 0
	v_mov_b32_e32 v33, 0
	v_mov_b32_e32 v34, 0
	v_mov_b32_e32 v35, 0
	v_mov_b32_e32 v36, 0
	v_mov_b32_e32 v37, 0
	v_mov_b32_e32 v38, 0
	v_mov_b32_e32 v39, 0
	v_mov_b32_e32 v40, 0
	v_mov_b32_e32 v41, 0
	v_mov_b32_e32 v42, 0
	v_mov_b32_e32 v43, 0
	v_mov_b32_e32 v44, 0
	v_mov_b32_e32 v45, 0
	v_mov_b32_e32 v46, 0
	v_mov_b32_e32 v47, 0
	v_mov_b32_e32 v48, 0
	v_mov_b32_e32 v49, 0
	v_mov_b32_e32 v50, 0
	v_mov_b32_e32 v51, 0
	v_mov_b32_e32 v52, 0
	v_mov_b32_e32 v53, 0
	v_mov_b32_e32 v54, 0
	v_mov_b32_e32 v55, 0
	v_mov_b32_e32 v56, 0
	v_mov_b32_e32 v57, 0
	v_mov_b32_e32 v58, 0
	v_mov_b32_e32 v59, 0
	v_mov_b32_e32 v60, 0
	v_mov_b32_e32 v61, 0
	v_mov_b32_e32 v62, 0
	v_mov_b32_e32 v63, 0
	v_mov_b32_e32 v64, 0
	v_mov_b32_e32 v65, 0
	v_mov_b32_e32 v66, 0
	v_mov_b32_e32 v67, 0
	s_mov_b32 s5, 0
; template <int NI, bool DEEP = true>
; DEV void gemm_tile(f32x16 (&acc)[2][NI], const bf16* __restrict__ A, int lda, const bf16* __restrict__ Bt, int ldb,
;                    int K, bf16* sA, bf16* sB) {
;     ...
;   G_LOAD(ra0, rb0, 0)
;   if (DEEP) {
;     if (64 < K) G_LOAD(ra1, rb1, 64)
;     for (int k0 = 0; k0 < K; k0 += 128) {
;       G_STEP(ra0, rb0, k0 + 128)
;       if (k0 + 64 < K) G_STEP(ra1, rb1, k0 + 192)
;     }
.Lotk_loop:
	s_waitcnt vmcnt(0)
	s_barrier
	s_add_u32 m0, s16, 0x8000
	s_nop 0
	global_load_lds_dwordx4 v68, s[98:99]
	s_add_u32 m0, s16, 0x8400
	s_add_u32 s14, s98, 0x4000
	s_addc_u32 s15, s99, 0
	global_load_lds_dwordx4 v69, s[14:15]
	s_add_u32 m0, s16, 0x8800
	s_add_u32 s14, s98, 0x8000
	s_addc_u32 s15, s99, 0
	global_load_lds_dwordx4 v68, s[14:15]
	s_add_u32 m0, s16, 0x8c00
	s_add_u32 s14, s98, 0xc000
	s_addc_u32 s15, s99, 0
	global_load_lds_dwordx4 v69, s[14:15]
	s_add_u32 m0, s16, 0xd840
	s_nop 0
	global_load_lds_dwordx4 v68, s[100:101]
	s_add_u32 m0, s16, 0xdc40
	s_add_u32 s14, s100, 0x4000
	s_addc_u32 s15, s101, 0
	global_load_lds_dwordx4 v69, s[14:15]
	s_add_u32 m0, s16, 0xe040
	s_add_u32 s14, s100, 0x8000
	s_addc_u32 s15, s101, 0
	global_load_lds_dwordx4 v68, s[14:15]
	s_add_u32 m0, s16, 0xe440
	s_add_u32 s14, s100, 0xc000
	s_addc_u32 s15, s101, 0
	global_load_lds_dwordx4 v69, s[14:15]
	s_add_u32 s98, s98, 0x80
	s_addc_u32 s99, s99, 0
	s_add_u32 s100, s100, 0x80
	s_addc_u32 s101, s101, 0
	ds_read_b128 v[88:91], v74 offset:0
	ds_read_b128 v[80:83], v70 offset:0
	ds_read_b128 v[84:87], v70 offset:4096
	ds_read_b128 v[92:95], v74 offset:4096
	s_waitcnt lgkmcnt(2)
	v_mfma_f32_32x32x16_bf16 v[52:67], v[88:91], v[80:83], v[52:67]
	ds_read_b128 v[104:107], v75 offset:0
	ds_read_b128 v[96:99], v71 offset:0
	s_waitcnt lgkmcnt(3)
	v_mfma_f32_32x32x16_bf16 v[20:35], v[88:91], v[84:87], v[20:35]
	ds_read_b128 v[100:103], v71 offset:4096
	s_waitcnt lgkmcnt(3)
	v_mfma_f32_32x32x16_bf16 v[36:51], v[92:95], v[80:83], v[36:51]
	ds_read_b128 v[108:111], v75 offset:4096
	v_mfma_f32_32x32x16_bf16 v[4:19], v[92:95], v[84:87], v[4:19]
	s_waitcnt lgkmcnt(2)
	v_mfma_f32_32x32x16_bf16 v[52:67], v[104:107], v[96:99], v[52:67]
	ds_read_b128 v[88:91], v76 offset:0
	ds_read_b128 v[80:83], v72 offset:0
	s_waitcnt lgkmcnt(3)
	v_mfma_f32_32x32x16_bf16 v[20:35], v[104:107], v[100:103], v[20:35]
	ds_read_b128 v[84:87], v72 offset:4096
	s_waitcnt lgkmcnt(3)
	v_mfma_f32_32x32x16_bf16 v[36:51], v[108:111], v[96:99], v[36:51]
	ds_read_b128 v[92:95], v76 offset:4096
	v_mfma_f32_32x32x16_bf16 v[4:19], v[108:111], v[100:103], v[4:19]
	s_waitcnt lgkmcnt(2)
	v_mfma_f32_32x32x16_bf16 v[52:67], v[88:91], v[80:83], v[52:67]
	ds_read_b128 v[104:107], v77 offset:0
	ds_read_b128 v[96:99], v73 offset:0
	s_waitcnt lgkmcnt(3)
	v_mfma_f32_32x32x16_bf16 v[20:35], v[88:91], v[84:87], v[20:35]
	ds_read_b128 v[100:103], v73 offset:4096
	s_waitcnt lgkmcnt(3)
	v_mfma_f32_32x32x16_bf16 v[36:51], v[92:95], v[80:83], v[36:51]
	ds_read_b128 v[108:111], v77 offset:4096
	v_mfma_f32_32x32x16_bf16 v[4:19], v[92:95], v[84:87], v[4:19]
	s_waitcnt lgkmcnt(2)
	v_mfma_f32_32x32x16_bf16 v[52:67], v[104:107], v[96:99], v[52:67]
	s_waitcnt lgkmcnt(1)
	v_mfma_f32_32x32x16_bf16 v[20:35], v[104:107], v[100:103], v[20:35]
	s_waitcnt lgkmcnt(0)
	v_mfma_f32_32x32x16_bf16 v[36:51], v[108:111], v[96:99], v[36:51]
	v_mfma_f32_32x32x16_bf16 v[4:19], v[108:111], v[100:103], v[4:19]
	s_waitcnt vmcnt(0)
	s_barrier
	s_cmp_eq_u32 s5, 7
	s_cbranch_scc1 .Lotk_nodma
	s_add_u32 m0, s16, 0x0
	s_nop 0
	global_load_lds_dwordx4 v68, s[98:99]
	s_add_u32 m0, s16, 0x400
	s_add_u32 s14, s98, 0x4000
	s_addc_u32 s15, s99, 0
	global_load_lds_dwordx4 v69, s[14:15]
	s_add_u32 m0, s16, 0x800
	s_add_u32 s14, s98, 0x8000
	s_addc_u32 s15, s99, 0
	global_load_lds_dwordx4 v68, s[14:15]
	s_add_u32 m0, s16, 0xc00
	s_add_u32 s14, s98, 0xc000
	s_addc_u32 s15, s99, 0
	global_load_lds_dwordx4 v69, s[14:15]
	s_add_u32 m0, s16, 0x4000
	s_nop 0
	global_load_lds_dwordx4 v68, s[100:101]
	s_add_u32 m0, s16, 0x4400
	s_add_u32 s14, s100, 0x4000
	s_addc_u32 s15, s101, 0
	global_load_lds_dwordx4 v69, s[14:15]
	s_add_u32 m0, s16, 0x4800
	s_add_u32 s14, s100, 0x8000
	s_addc_u32 s15, s101, 0
	global_load_lds_dwordx4 v68, s[14:15]
	s_add_u32 m0, s16, 0x4c00
	s_add_u32 s14, s100, 0xc000
	s_addc_u32 s15, s101, 0
	global_load_lds_dwordx4 v69, s[14:15]
	s_add_u32 s98, s98, 0x80
	s_addc_u32 s99, s99, 0
	s_add_u32 s100, s100, 0x80
	s_addc_u32 s101, s101, 0
.Lotk_nodma:
	ds_read_b128 v[88:91], v74 offset:38976
	ds_read_b128 v[80:83], v70 offset:32768
	ds_read_b128 v[84:87], v70 offset:36864
	ds_read_b128 v[92:95], v74 offset:43072
	s_waitcnt lgkmcnt(2)
	v_mfma_f32_32x32x16_bf16 v[52:67], v[88:91], v[80:83], v[52:67]
	ds_read_b128 v[104:107], v75 offset:38976
	ds_read_b128 v[96:99], v71 offset:32768
	s_waitcnt lgkmcnt(3)
	v_mfma_f32_32x32x16_bf16 v[20:35], v[88:91], v[84:87], v[20:35]
	ds_read_b128 v[100:103], v71 offset:36864
	s_waitcnt lgkmcnt(3)
	v_mfma_f32_32x32x16_bf16 v[36:51], v[92:95], v[80:83], v[36:51]
	ds_read_b128 v[108:111], v75 offset:43072
	v_mfma_f32_32x32x16_bf16 v[4:19], v[92:95], v[84:87], v[4:19]
	s_waitcnt lgkmcnt(2)
	v_mfma_f32_32x32x16_bf16 v[52:67], v[104:107], v[96:99], v[52:67]
	ds_read_b128 v[88:91], v76 offset:38976
	ds_read_b128 v[80:83], v72 offset:32768
	s_waitcnt lgkmcnt(3)
	v_mfma_f32_32x32x16_bf16 v[20:35], v[104:107], v[100:103], v[20:35]
	ds_read_b128 v[84:87], v72 offset:36864
	s_waitcnt lgkmcnt(3)
	v_mfma_f32_32x32x16_bf16 v[36:51], v[108:111], v[96:99], v[36:51]
	ds_read_b128 v[92:95], v76 offset:43072
	v_mfma_f32_32x32x16_bf16 v[4:19], v[108:111], v[100:103], v[4:19]
	s_waitcnt lgkmcnt(2)
	v_mfma_f32_32x32x16_bf16 v[52:67], v[88:91], v[80:83], v[52:67]
	ds_read_b128 v[104:107], v77 offset:38976
	ds_read_b128 v[96:99], v73 offset:32768
	s_waitcnt lgkmcnt(3)
	v_mfma_f32_32x32x16_bf16 v[20:35], v[88:91], v[84:87], v[20:35]
	ds_read_b128 v[100:103], v73 offset:36864
	s_waitcnt lgkmcnt(3)
	v_mfma_f32_32x32x16_bf16 v[36:51], v[92:95], v[80:83], v[36:51]
	ds_read_b128 v[108:111], v77 offset:43072
	v_mfma_f32_32x32x16_bf16 v[4:19], v[92:95], v[84:87], v[4:19]
	s_waitcnt lgkmcnt(2)
	v_mfma_f32_32x32x16_bf16 v[52:67], v[104:107], v[96:99], v[52:67]
	s_waitcnt lgkmcnt(1)
	v_mfma_f32_32x32x16_bf16 v[20:35], v[104:107], v[100:103], v[20:35]
	s_waitcnt lgkmcnt(0)
	v_mfma_f32_32x32x16_bf16 v[36:51], v[108:111], v[96:99], v[36:51]
	v_mfma_f32_32x32x16_bf16 v[4:19], v[108:111], v[100:103], v[4:19]
	s_add_i32 s5, s5, 1
	s_cmp_lt_u32 s5, 8
	s_cbranch_scc1 .Lotk_loop
	s_nop 7
	s_nop 7
